# KVDOWN epilogue ssq-load hoist + final RMSNorm loop rewritten with hoisted gain loads and next-row prefetch
# speedup vs baseline: 1.0980x; 1.0980x over previous
.LBB0_1053:
	v_lshl_add_u32 v150, s10, 8, v153
	v_ashrrev_i32_e32 v151, 31, v150
	v_lshl_add_u64 v[162:163], v[150:151], 2, s[16:17]
	global_load_dword v234, v[162:163], off offset:64
	global_load_dword v235, v[162:163], off offset:128
	global_load_dword v236, v[162:163], off offset:192
	global_load_dword v237, v[162:163], off offset:512
	global_load_dword v238, v[162:163], off offset:576
	global_load_dword v239, v[162:163], off offset:640
	global_load_dword v240, v[162:163], off offset:704
	global_load_dword v152, v[162:163], off
	s_cmp_lg_u32 s8, 0
	s_cselect_b64 s[56:57], -1, 0
	v_cndmask_b32_e64 v161, 0, 1, s[46:47]
	s_and_b64 vcc, exec, s[56:57]
	v_cmp_ne_u32_e64 s[8:9], 1, v161
	s_waitcnt vmcnt(0)
	v_fmamk_f32 v152, v152, 0x3a800000, v159
	v_rsq_f32_e32 v152, v152
	s_cbranch_vccz .LBB0_1057
	s_and_b64 vcc, exec, s[8:9]
	s_cbranch_vccnz .LBB0_1056
	v_lshlrev_b32_e32 v161, 5, v150
	v_and_or_b32 v161, v161, s75, v154
	v_lshlrev_b32_e32 v161, 3, v161
	global_load_dwordx4 v[162:165], v161, s[26:27]
	global_load_dwordx4 v[166:169], v161, s[26:27] offset:16
	global_load_dwordx4 v[170:173], v161, s[26:27] offset:32
	global_load_dwordx4 v[174:177], v161, s[26:27] offset:48
	v_mov_b32_e32 v186, v128
	v_mov_b32_e32 v187, v121
	v_mov_b32_e32 v188, v120
	v_mov_b32_e32 v189, v129
	v_mov_b32_e32 v178, v126
	v_mov_b32_e32 v179, v119
	v_mov_b32_e32 v180, v118
	v_mov_b32_e32 v181, v127
	v_mov_b32_e32 v182, v122
	v_mov_b32_e32 v183, v115
	v_mov_b32_e32 v184, v114
	v_mov_b32_e32 v185, v123
	v_mov_b32_e32 v190, v124
	v_mov_b32_e32 v191, v117
	v_mov_b32_e32 v192, v116
	v_mov_b32_e32 v193, v125
	v_pk_mul_f32 v[186:187], v[186:187], v[152:153] op_sel_hi:[1,0]
	v_pk_mul_f32 v[188:189], v[188:189], v[152:153] op_sel_hi:[1,0]
	v_pk_mul_f32 v[178:179], v[178:179], v[152:153] op_sel_hi:[1,0]
	v_pk_mul_f32 v[180:181], v[180:181], v[152:153] op_sel_hi:[1,0]
	v_pk_mul_f32 v[182:183], v[182:183], v[152:153] op_sel_hi:[1,0]
	v_pk_mul_f32 v[184:185], v[184:185], v[152:153] op_sel_hi:[1,0]
	v_pk_mul_f32 v[190:191], v[190:191], v[152:153] op_sel_hi:[1,0]
	v_pk_mul_f32 v[192:193], v[192:193], v[152:153] op_sel_hi:[1,0]
	v_mov_b32_e32 v199, v189
	v_mov_b32_e32 v195, v181
	v_mov_b32_e32 v197, v185
	v_mov_b32_e32 v198, v186
	v_mov_b32_e32 v201, v193
	v_mov_b32_e32 v194, v178
	v_mov_b32_e32 v196, v182
	v_mov_b32_e32 v200, v190
	s_waitcnt vmcnt(3)
	v_mov_b32_e32 v210, v162
	v_mov_b32_e32 v212, v162
	s_waitcnt vmcnt(1)
	v_mov_b32_e32 v206, v171
	v_mov_b32_e32 v207, v172
	v_mov_b32_e32 v162, v170
	v_mov_b32_e32 v214, v170
	v_mov_b32_e32 v215, v172
	v_mov_b32_e32 v172, v171
	v_mov_b32_e32 v170, v166
	v_mov_b32_e32 v171, v169
	v_mov_b32_e32 v202, v163
	v_mov_b32_e32 v203, v164
	v_mov_b32_e32 v204, v167
	v_mov_b32_e32 v205, v168
	v_mov_b32_e32 v211, v165
	v_mov_b32_e32 v213, v164
	v_mov_b32_e32 v164, v163
	v_mov_b32_e32 v163, v173
	v_mov_b32_e32 v216, v166
	v_mov_b32_e32 v217, v168
	v_mov_b32_e32 v168, v167
	s_waitcnt vmcnt(0)
	v_mov_b32_e32 v166, v174
	v_mov_b32_e32 v167, v177
	v_pk_mul_f32 v[170:171], v[188:189], v[170:171]
	v_mov_b32_e32 v189, v187
	v_mov_b32_e32 v208, v175
	v_mov_b32_e32 v209, v176
	v_mov_b32_e32 v218, v174
	v_mov_b32_e32 v219, v176
	v_mov_b32_e32 v176, v175
	v_pk_mul_f32 v[174:175], v[180:181], v[210:211]
	v_mov_b32_e32 v181, v179
	v_pk_mul_f32 v[162:163], v[184:185], v[162:163]
	v_mov_b32_e32 v185, v183
	v_pk_mul_f32 v[166:167], v[192:193], v[166:167]
	v_mov_b32_e32 v193, v191
	v_pk_mul_f32 v[168:169], v[188:189], v[168:169]
	v_pk_fma_f32 v[174:175], v[178:179], v[202:203], v[174:175]
	v_pk_mul_f32 v[164:165], v[180:181], v[164:165]
	v_pk_fma_f32 v[178:179], v[182:183], v[206:207], v[162:163]
	v_pk_mul_f32 v[162:163], v[184:185], v[172:173]
	v_pk_mul_f32 v[172:173], v[192:193], v[176:177]
	v_pk_fma_f32 v[168:169], v[198:199], v[216:217], v[168:169] neg_lo:[0,0,1] neg_hi:[0,0,1]
	v_pk_fma_f32 v[164:165], v[194:195], v[212:213], v[164:165] neg_lo:[0,0,1] neg_hi:[0,0,1]
	v_pk_fma_f32 v[176:177], v[196:197], v[214:215], v[162:163] neg_lo:[0,0,1] neg_hi:[0,0,1]
	v_pk_fma_f32 v[172:173], v[200:201], v[218:219], v[172:173] neg_lo:[0,0,1] neg_hi:[0,0,1]
	v_cvt_pk_bf16_f32 v163, v168, v169
	v_lshlrev_b64 v[168:169], 7, v[150:151]
	v_pk_fma_f32 v[170:171], v[186:187], v[204:205], v[170:171]
	v_pk_fma_f32 v[166:167], v[190:191], v[208:209], v[166:167]
	v_cvt_pk_bf16_f32 v162, v164, v165
	v_cvt_pk_bf16_f32 v164, v176, v177
	v_cvt_pk_bf16_f32 v165, v172, v173
	v_lshl_add_u64 v[168:169], v[138:139], 0, v[168:169]
	global_store_dwordx4 v[168:169], v[162:165], off
	s_nop 1
	v_cvt_pk_bf16_f32 v162, v174, v175
	v_cvt_pk_bf16_f32 v163, v170, v171
	v_cvt_pk_bf16_f32 v164, v178, v179
	v_cvt_pk_bf16_f32 v165, v166, v167
	global_store_dwordx4 v[168:169], v[162:165], off offset:64

.LBB0_1061:
	v_or_b32_e32 v114, 16, v150
	s_waitcnt lgkmcnt(0)
	v_ashrrev_i32_e32 v115, 31, v114
	v_cndmask_b32_e64 v117, 0, 1, s[56:57]
	v_cmp_ne_u32_e64 s[10:11], 1, v117
	s_andn2_b64 vcc, exec, s[56:57]
	v_fmamk_f32 v116, v234, 0x3a800000, v159
	v_rsq_f32_e32 v116, v116
	s_cbranch_vccnz .LBB0_1065
	s_and_b64 vcc, exec, s[8:9]
	s_cbranch_vccnz .LBB0_1064
	v_lshlrev_b32_e32 v117, 5, v114
	v_and_or_b32 v117, v117, s76, v154
	v_lshlrev_b32_e32 v117, 3, v117
	global_load_dwordx4 v[118:121], v117, s[26:27]
	global_load_dwordx4 v[122:125], v117, s[26:27] offset:16
	global_load_dwordx4 v[126:129], v117, s[26:27] offset:32
	global_load_dwordx4 v[162:165], v117, s[26:27] offset:48
	v_mov_b32_e32 v174, v112
	v_mov_b32_e32 v175, v105
	v_mov_b32_e32 v176, v104
	v_mov_b32_e32 v177, v113
	v_mov_b32_e32 v166, v110
	v_mov_b32_e32 v167, v103
	v_mov_b32_e32 v168, v102
	v_mov_b32_e32 v169, v111
	v_mov_b32_e32 v170, v106
	v_mov_b32_e32 v171, v99
	v_mov_b32_e32 v172, v98
	v_mov_b32_e32 v173, v107
	v_mov_b32_e32 v178, v108
	v_mov_b32_e32 v179, v101
	v_mov_b32_e32 v180, v100
	v_mov_b32_e32 v181, v109
	v_pk_mul_f32 v[174:175], v[174:175], v[116:117] op_sel_hi:[1,0]
	v_pk_mul_f32 v[176:177], v[176:177], v[116:117] op_sel_hi:[1,0]
	v_pk_mul_f32 v[166:167], v[166:167], v[116:117] op_sel_hi:[1,0]
	v_pk_mul_f32 v[168:169], v[168:169], v[116:117] op_sel_hi:[1,0]
	v_pk_mul_f32 v[170:171], v[170:171], v[116:117] op_sel_hi:[1,0]
	v_pk_mul_f32 v[172:173], v[172:173], v[116:117] op_sel_hi:[1,0]
	v_pk_mul_f32 v[178:179], v[178:179], v[116:117] op_sel_hi:[1,0]
	v_pk_mul_f32 v[180:181], v[180:181], v[116:117] op_sel_hi:[1,0]
	v_mov_b32_e32 v187, v177
	v_mov_b32_e32 v183, v169
	v_mov_b32_e32 v185, v173
	v_mov_b32_e32 v186, v174
	v_mov_b32_e32 v189, v181
	v_mov_b32_e32 v182, v166
	v_mov_b32_e32 v184, v170
	v_mov_b32_e32 v188, v178
	s_waitcnt vmcnt(3)
	v_mov_b32_e32 v198, v118
	v_mov_b32_e32 v200, v118
	s_waitcnt vmcnt(1)
	v_mov_b32_e32 v194, v127
	v_mov_b32_e32 v195, v128
	v_mov_b32_e32 v118, v126
	v_mov_b32_e32 v202, v126
	v_mov_b32_e32 v203, v128
	v_mov_b32_e32 v128, v127
	v_mov_b32_e32 v126, v122
	v_mov_b32_e32 v127, v125
	v_mov_b32_e32 v190, v119
	v_mov_b32_e32 v191, v120
	v_mov_b32_e32 v192, v123
	v_mov_b32_e32 v193, v124
	v_mov_b32_e32 v199, v121
	v_mov_b32_e32 v201, v120
	v_mov_b32_e32 v120, v119
	v_mov_b32_e32 v119, v129
	v_mov_b32_e32 v204, v122
	v_mov_b32_e32 v205, v124
	v_mov_b32_e32 v124, v123
	s_waitcnt vmcnt(0)
	v_mov_b32_e32 v122, v162
	v_mov_b32_e32 v123, v165
	v_pk_mul_f32 v[126:127], v[176:177], v[126:127]
	v_mov_b32_e32 v177, v175
	v_mov_b32_e32 v196, v163
	v_mov_b32_e32 v197, v164
	v_mov_b32_e32 v206, v162
	v_mov_b32_e32 v207, v164
	v_mov_b32_e32 v164, v163
	v_pk_mul_f32 v[162:163], v[168:169], v[198:199]
	v_mov_b32_e32 v169, v167
	v_pk_mul_f32 v[118:119], v[172:173], v[118:119]
	v_mov_b32_e32 v173, v171
	v_pk_mul_f32 v[122:123], v[180:181], v[122:123]
	v_mov_b32_e32 v181, v179
	v_pk_mul_f32 v[124:125], v[176:177], v[124:125]
	v_pk_fma_f32 v[162:163], v[166:167], v[190:191], v[162:163]
	v_pk_mul_f32 v[120:121], v[168:169], v[120:121]
	v_pk_fma_f32 v[166:167], v[170:171], v[194:195], v[118:119]
	v_pk_mul_f32 v[118:119], v[172:173], v[128:129]
	v_pk_mul_f32 v[128:129], v[180:181], v[164:165]
	v_pk_fma_f32 v[124:125], v[186:187], v[204:205], v[124:125] neg_lo:[0,0,1] neg_hi:[0,0,1]
	v_pk_fma_f32 v[120:121], v[182:183], v[200:201], v[120:121] neg_lo:[0,0,1] neg_hi:[0,0,1]
	v_pk_fma_f32 v[164:165], v[184:185], v[202:203], v[118:119] neg_lo:[0,0,1] neg_hi:[0,0,1]
	v_pk_fma_f32 v[128:129], v[188:189], v[206:207], v[128:129] neg_lo:[0,0,1] neg_hi:[0,0,1]
	v_cvt_pk_bf16_f32 v119, v124, v125
	v_lshlrev_b64 v[124:125], 7, v[114:115]
	v_pk_fma_f32 v[126:127], v[174:175], v[192:193], v[126:127]
	v_pk_fma_f32 v[122:123], v[178:179], v[196:197], v[122:123]
	v_cvt_pk_bf16_f32 v118, v120, v121
	v_cvt_pk_bf16_f32 v120, v164, v165
	v_cvt_pk_bf16_f32 v121, v128, v129
	v_lshl_add_u64 v[124:125], v[138:139], 0, v[124:125]
	global_store_dwordx4 v[124:125], v[118:121], off
	s_nop 1
	v_cvt_pk_bf16_f32 v118, v162, v163
	v_cvt_pk_bf16_f32 v119, v126, v127
	v_cvt_pk_bf16_f32 v120, v166, v167
	v_cvt_pk_bf16_f32 v121, v122, v123
	global_store_dwordx4 v[124:125], v[118:121], off offset:64

.LBB0_1069:
	v_or_b32_e32 v98, 32, v150
	s_waitcnt lgkmcnt(0)
	v_ashrrev_i32_e32 v99, 31, v98
	s_and_b64 vcc, exec, s[10:11]
	v_fmamk_f32 v100, v235, 0x3a800000, v159
	v_rsq_f32_e32 v100, v100
	s_cbranch_vccnz .LBB0_1073
	s_and_b64 vcc, exec, s[8:9]
	s_cbranch_vccnz .LBB0_1072
	v_lshlrev_b32_e32 v101, 5, v98
	v_and_or_b32 v101, v101, s77, v154
	v_lshlrev_b32_e32 v101, 3, v101
	global_load_dwordx4 v[102:105], v101, s[26:27]
	global_load_dwordx4 v[106:109], v101, s[26:27] offset:16
	global_load_dwordx4 v[110:113], v101, s[26:27] offset:32
	global_load_dwordx4 v[114:117], v101, s[26:27] offset:48
	v_mov_b32_e32 v126, v96
	v_mov_b32_e32 v127, v89
	v_mov_b32_e32 v128, v88
	v_mov_b32_e32 v129, v97
	v_mov_b32_e32 v118, v94
	v_mov_b32_e32 v119, v87
	v_mov_b32_e32 v120, v86
	v_mov_b32_e32 v121, v95
	v_mov_b32_e32 v122, v90
	v_mov_b32_e32 v123, v83
	v_mov_b32_e32 v124, v82
	v_mov_b32_e32 v125, v91
	v_mov_b32_e32 v162, v92
	v_mov_b32_e32 v163, v85
	v_mov_b32_e32 v164, v84
	v_mov_b32_e32 v165, v93
	v_pk_mul_f32 v[126:127], v[126:127], v[100:101] op_sel_hi:[1,0]
	v_pk_mul_f32 v[128:129], v[128:129], v[100:101] op_sel_hi:[1,0]
	v_pk_mul_f32 v[118:119], v[118:119], v[100:101] op_sel_hi:[1,0]
	v_pk_mul_f32 v[120:121], v[120:121], v[100:101] op_sel_hi:[1,0]
	v_pk_mul_f32 v[122:123], v[122:123], v[100:101] op_sel_hi:[1,0]
	v_pk_mul_f32 v[124:125], v[124:125], v[100:101] op_sel_hi:[1,0]
	v_pk_mul_f32 v[162:163], v[162:163], v[100:101] op_sel_hi:[1,0]
	v_pk_mul_f32 v[164:165], v[164:165], v[100:101] op_sel_hi:[1,0]
	v_mov_b32_e32 v171, v129
	v_mov_b32_e32 v167, v121
	v_mov_b32_e32 v169, v125
	v_mov_b32_e32 v170, v126
	v_mov_b32_e32 v173, v165
	v_mov_b32_e32 v166, v118
	v_mov_b32_e32 v168, v122
	v_mov_b32_e32 v172, v162
	s_waitcnt vmcnt(3)
	v_mov_b32_e32 v182, v102
	v_mov_b32_e32 v184, v102
	s_waitcnt vmcnt(1)
	v_mov_b32_e32 v178, v111
	v_mov_b32_e32 v179, v112
	v_mov_b32_e32 v102, v110
	v_mov_b32_e32 v186, v110
	v_mov_b32_e32 v187, v112
	v_mov_b32_e32 v112, v111
	v_mov_b32_e32 v110, v106
	v_mov_b32_e32 v111, v109
	v_mov_b32_e32 v174, v103
	v_mov_b32_e32 v175, v104
	v_mov_b32_e32 v176, v107
	v_mov_b32_e32 v177, v108
	v_mov_b32_e32 v183, v105
	v_mov_b32_e32 v185, v104
	v_mov_b32_e32 v104, v103
	v_mov_b32_e32 v103, v113
	v_mov_b32_e32 v188, v106
	v_mov_b32_e32 v189, v108
	v_mov_b32_e32 v108, v107
	s_waitcnt vmcnt(0)
	v_mov_b32_e32 v106, v114
	v_mov_b32_e32 v107, v117
	v_pk_mul_f32 v[110:111], v[128:129], v[110:111]
	v_mov_b32_e32 v129, v127
	v_mov_b32_e32 v180, v115
	v_mov_b32_e32 v181, v116
	v_mov_b32_e32 v190, v114
	v_mov_b32_e32 v191, v116
	v_mov_b32_e32 v116, v115
	v_pk_mul_f32 v[114:115], v[120:121], v[182:183]
	v_mov_b32_e32 v121, v119
	v_pk_mul_f32 v[102:103], v[124:125], v[102:103]
	v_mov_b32_e32 v125, v123
	v_pk_mul_f32 v[106:107], v[164:165], v[106:107]
	v_mov_b32_e32 v165, v163
	v_pk_mul_f32 v[108:109], v[128:129], v[108:109]
	v_pk_fma_f32 v[114:115], v[118:119], v[174:175], v[114:115]
	v_pk_mul_f32 v[104:105], v[120:121], v[104:105]
	v_pk_fma_f32 v[118:119], v[122:123], v[178:179], v[102:103]
	v_pk_mul_f32 v[102:103], v[124:125], v[112:113]
	v_pk_mul_f32 v[112:113], v[164:165], v[116:117]
	v_pk_fma_f32 v[108:109], v[170:171], v[188:189], v[108:109] neg_lo:[0,0,1] neg_hi:[0,0,1]
	v_pk_fma_f32 v[104:105], v[166:167], v[184:185], v[104:105] neg_lo:[0,0,1] neg_hi:[0,0,1]
	v_pk_fma_f32 v[116:117], v[168:169], v[186:187], v[102:103] neg_lo:[0,0,1] neg_hi:[0,0,1]
	v_pk_fma_f32 v[112:113], v[172:173], v[190:191], v[112:113] neg_lo:[0,0,1] neg_hi:[0,0,1]
	v_cvt_pk_bf16_f32 v103, v108, v109
	v_lshlrev_b64 v[108:109], 7, v[98:99]
	v_pk_fma_f32 v[110:111], v[126:127], v[176:177], v[110:111]
	v_pk_fma_f32 v[106:107], v[162:163], v[180:181], v[106:107]
	v_cvt_pk_bf16_f32 v102, v104, v105
	v_cvt_pk_bf16_f32 v104, v116, v117
	v_cvt_pk_bf16_f32 v105, v112, v113
	v_lshl_add_u64 v[108:109], v[138:139], 0, v[108:109]
	global_store_dwordx4 v[108:109], v[102:105], off
	s_nop 1
	v_cvt_pk_bf16_f32 v102, v114, v115
	v_cvt_pk_bf16_f32 v103, v110, v111
	v_cvt_pk_bf16_f32 v104, v118, v119
	v_cvt_pk_bf16_f32 v105, v106, v107
	global_store_dwordx4 v[108:109], v[102:105], off offset:64

.LBB0_1077:
	v_or_b32_e32 v82, 48, v150
	s_waitcnt lgkmcnt(0)
	v_ashrrev_i32_e32 v83, 31, v82
	s_and_b64 vcc, exec, s[10:11]
	v_fmamk_f32 v84, v236, 0x3a800000, v159
	v_rsq_f32_e32 v84, v84
	s_cbranch_vccnz .LBB0_1081
	s_and_b64 vcc, exec, s[8:9]
	s_cbranch_vccnz .LBB0_1080
	v_lshlrev_b32_e32 v85, 5, v82
	v_and_or_b32 v85, v85, s78, v154
	v_lshlrev_b32_e32 v85, 3, v85
	global_load_dwordx4 v[86:89], v85, s[26:27]
	global_load_dwordx4 v[90:93], v85, s[26:27] offset:16
	global_load_dwordx4 v[94:97], v85, s[26:27] offset:32
	global_load_dwordx4 v[98:101], v85, s[26:27] offset:48
	v_mov_b32_e32 v110, v80
	v_mov_b32_e32 v111, v73
	v_mov_b32_e32 v112, v72
	v_mov_b32_e32 v113, v81
	v_mov_b32_e32 v102, v78
	v_mov_b32_e32 v103, v71
	v_mov_b32_e32 v104, v70
	v_mov_b32_e32 v105, v79
	v_mov_b32_e32 v106, v74
	v_mov_b32_e32 v107, v67
	v_mov_b32_e32 v108, v66
	v_mov_b32_e32 v109, v75
	v_mov_b32_e32 v114, v76
	v_mov_b32_e32 v115, v69
	v_mov_b32_e32 v116, v68
	v_mov_b32_e32 v117, v77
	v_pk_mul_f32 v[110:111], v[110:111], v[84:85] op_sel_hi:[1,0]
	v_pk_mul_f32 v[112:113], v[112:113], v[84:85] op_sel_hi:[1,0]
	v_pk_mul_f32 v[102:103], v[102:103], v[84:85] op_sel_hi:[1,0]
	v_pk_mul_f32 v[104:105], v[104:105], v[84:85] op_sel_hi:[1,0]
	v_pk_mul_f32 v[106:107], v[106:107], v[84:85] op_sel_hi:[1,0]
	v_pk_mul_f32 v[108:109], v[108:109], v[84:85] op_sel_hi:[1,0]
	v_pk_mul_f32 v[114:115], v[114:115], v[84:85] op_sel_hi:[1,0]
	v_pk_mul_f32 v[116:117], v[116:117], v[84:85] op_sel_hi:[1,0]
	v_mov_b32_e32 v123, v113
	v_mov_b32_e32 v119, v105
	v_mov_b32_e32 v121, v109
	v_mov_b32_e32 v122, v110
	v_mov_b32_e32 v125, v117
	v_mov_b32_e32 v118, v102
	v_mov_b32_e32 v120, v106
	v_mov_b32_e32 v124, v114
	s_waitcnt vmcnt(3)
	v_mov_b32_e32 v166, v86
	v_mov_b32_e32 v168, v86
	s_waitcnt vmcnt(1)
	v_mov_b32_e32 v162, v95
	v_mov_b32_e32 v163, v96
	v_mov_b32_e32 v86, v94
	v_mov_b32_e32 v170, v94
	v_mov_b32_e32 v171, v96
	v_mov_b32_e32 v96, v95
	v_mov_b32_e32 v94, v90
	v_mov_b32_e32 v95, v93
	v_mov_b32_e32 v126, v87
	v_mov_b32_e32 v127, v88
	v_mov_b32_e32 v128, v91
	v_mov_b32_e32 v129, v92
	v_mov_b32_e32 v167, v89
	v_mov_b32_e32 v169, v88
	v_mov_b32_e32 v88, v87
	v_mov_b32_e32 v87, v97
	v_mov_b32_e32 v172, v90
	v_mov_b32_e32 v173, v92
	v_mov_b32_e32 v92, v91
	s_waitcnt vmcnt(0)
	v_mov_b32_e32 v90, v98
	v_mov_b32_e32 v91, v101
	v_pk_mul_f32 v[94:95], v[112:113], v[94:95]
	v_mov_b32_e32 v113, v111
	v_mov_b32_e32 v164, v99
	v_mov_b32_e32 v165, v100
	v_mov_b32_e32 v174, v98
	v_mov_b32_e32 v175, v100
	v_mov_b32_e32 v100, v99
	v_pk_mul_f32 v[98:99], v[104:105], v[166:167]
	v_mov_b32_e32 v105, v103
	v_pk_mul_f32 v[86:87], v[108:109], v[86:87]
	v_mov_b32_e32 v109, v107
	v_pk_mul_f32 v[90:91], v[116:117], v[90:91]
	v_mov_b32_e32 v117, v115
	v_pk_mul_f32 v[92:93], v[112:113], v[92:93]
	v_pk_fma_f32 v[98:99], v[102:103], v[126:127], v[98:99]
	v_pk_mul_f32 v[88:89], v[104:105], v[88:89]
	v_pk_fma_f32 v[102:103], v[106:107], v[162:163], v[86:87]
	v_pk_mul_f32 v[86:87], v[108:109], v[96:97]
	v_pk_mul_f32 v[96:97], v[116:117], v[100:101]
	v_pk_fma_f32 v[92:93], v[122:123], v[172:173], v[92:93] neg_lo:[0,0,1] neg_hi:[0,0,1]
	v_pk_fma_f32 v[88:89], v[118:119], v[168:169], v[88:89] neg_lo:[0,0,1] neg_hi:[0,0,1]
	v_pk_fma_f32 v[100:101], v[120:121], v[170:171], v[86:87] neg_lo:[0,0,1] neg_hi:[0,0,1]
	v_pk_fma_f32 v[96:97], v[124:125], v[174:175], v[96:97] neg_lo:[0,0,1] neg_hi:[0,0,1]
	v_cvt_pk_bf16_f32 v87, v92, v93
	v_lshlrev_b64 v[92:93], 7, v[82:83]
	v_pk_fma_f32 v[94:95], v[110:111], v[128:129], v[94:95]
	v_pk_fma_f32 v[90:91], v[114:115], v[164:165], v[90:91]
	v_cvt_pk_bf16_f32 v86, v88, v89
	v_cvt_pk_bf16_f32 v88, v100, v101
	v_cvt_pk_bf16_f32 v89, v96, v97
	v_lshl_add_u64 v[92:93], v[138:139], 0, v[92:93]
	global_store_dwordx4 v[92:93], v[86:89], off
	s_nop 1
	v_cvt_pk_bf16_f32 v86, v98, v99
	v_cvt_pk_bf16_f32 v87, v94, v95
	v_cvt_pk_bf16_f32 v88, v102, v103
	v_cvt_pk_bf16_f32 v89, v90, v91
	global_store_dwordx4 v[92:93], v[86:89], off offset:64

.LBB0_1085:
	v_add_u32_e32 v66, 0x80, v150
	s_waitcnt lgkmcnt(0)
	v_ashrrev_i32_e32 v67, 31, v66
	s_and_b64 vcc, exec, s[10:11]
	v_fmamk_f32 v68, v237, 0x3a800000, v159
	v_rsq_f32_e32 v68, v68
	s_cbranch_vccnz .LBB0_1089
	s_and_b64 vcc, exec, s[8:9]
	s_cbranch_vccnz .LBB0_1088
	v_lshlrev_b32_e32 v69, 5, v66
	v_and_or_b32 v69, v69, s75, v154
	v_lshlrev_b32_e32 v69, 3, v69
	global_load_dwordx4 v[70:73], v69, s[26:27]
	global_load_dwordx4 v[74:77], v69, s[26:27] offset:16
	global_load_dwordx4 v[78:81], v69, s[26:27] offset:32
	global_load_dwordx4 v[82:85], v69, s[26:27] offset:48
	v_mov_b32_e32 v94, v64
	v_mov_b32_e32 v95, v57
	v_mov_b32_e32 v96, v56
	v_mov_b32_e32 v97, v65
	v_mov_b32_e32 v86, v62
	v_mov_b32_e32 v87, v55
	v_mov_b32_e32 v88, v54
	v_mov_b32_e32 v89, v63
	v_mov_b32_e32 v90, v58
	v_mov_b32_e32 v91, v51
	v_mov_b32_e32 v92, v50
	v_mov_b32_e32 v93, v59
	v_mov_b32_e32 v98, v60
	v_mov_b32_e32 v99, v53
	v_mov_b32_e32 v100, v52
	v_mov_b32_e32 v101, v61
	v_pk_mul_f32 v[94:95], v[94:95], v[68:69] op_sel_hi:[1,0]
	v_pk_mul_f32 v[96:97], v[96:97], v[68:69] op_sel_hi:[1,0]
	v_pk_mul_f32 v[86:87], v[86:87], v[68:69] op_sel_hi:[1,0]
	v_pk_mul_f32 v[88:89], v[88:89], v[68:69] op_sel_hi:[1,0]
	v_pk_mul_f32 v[90:91], v[90:91], v[68:69] op_sel_hi:[1,0]
	v_pk_mul_f32 v[92:93], v[92:93], v[68:69] op_sel_hi:[1,0]
	v_pk_mul_f32 v[98:99], v[98:99], v[68:69] op_sel_hi:[1,0]
	v_pk_mul_f32 v[100:101], v[100:101], v[68:69] op_sel_hi:[1,0]
	v_mov_b32_e32 v107, v97
	v_mov_b32_e32 v103, v89
	v_mov_b32_e32 v105, v93
	v_mov_b32_e32 v106, v94
	v_mov_b32_e32 v109, v101
	v_mov_b32_e32 v102, v86
	v_mov_b32_e32 v104, v90
	v_mov_b32_e32 v108, v98
	s_waitcnt vmcnt(3)
	v_mov_b32_e32 v118, v70
	v_mov_b32_e32 v120, v70
	s_waitcnt vmcnt(1)
	v_mov_b32_e32 v114, v79
	v_mov_b32_e32 v115, v80
	v_mov_b32_e32 v70, v78
	v_mov_b32_e32 v122, v78
	v_mov_b32_e32 v123, v80
	v_mov_b32_e32 v80, v79
	v_mov_b32_e32 v78, v74
	v_mov_b32_e32 v79, v77
	v_mov_b32_e32 v110, v71
	v_mov_b32_e32 v111, v72
	v_mov_b32_e32 v112, v75
	v_mov_b32_e32 v113, v76
	v_mov_b32_e32 v119, v73
	v_mov_b32_e32 v121, v72
	v_mov_b32_e32 v72, v71
	v_mov_b32_e32 v71, v81
	v_mov_b32_e32 v124, v74
	v_mov_b32_e32 v125, v76
	v_mov_b32_e32 v76, v75
	s_waitcnt vmcnt(0)
	v_mov_b32_e32 v74, v82
	v_mov_b32_e32 v75, v85
	v_pk_mul_f32 v[78:79], v[96:97], v[78:79]
	v_mov_b32_e32 v97, v95
	v_mov_b32_e32 v116, v83
	v_mov_b32_e32 v117, v84
	v_mov_b32_e32 v126, v82
	v_mov_b32_e32 v127, v84
	v_mov_b32_e32 v84, v83
	v_pk_mul_f32 v[82:83], v[88:89], v[118:119]
	v_mov_b32_e32 v89, v87
	v_pk_mul_f32 v[70:71], v[92:93], v[70:71]
	v_mov_b32_e32 v93, v91
	v_pk_mul_f32 v[74:75], v[100:101], v[74:75]
	v_mov_b32_e32 v101, v99
	v_pk_mul_f32 v[76:77], v[96:97], v[76:77]
	v_pk_fma_f32 v[82:83], v[86:87], v[110:111], v[82:83]
	v_pk_mul_f32 v[72:73], v[88:89], v[72:73]
	v_pk_fma_f32 v[86:87], v[90:91], v[114:115], v[70:71]
	v_pk_mul_f32 v[70:71], v[92:93], v[80:81]
	v_pk_mul_f32 v[80:81], v[100:101], v[84:85]
	v_pk_fma_f32 v[76:77], v[106:107], v[124:125], v[76:77] neg_lo:[0,0,1] neg_hi:[0,0,1]
	v_pk_fma_f32 v[72:73], v[102:103], v[120:121], v[72:73] neg_lo:[0,0,1] neg_hi:[0,0,1]
	v_pk_fma_f32 v[84:85], v[104:105], v[122:123], v[70:71] neg_lo:[0,0,1] neg_hi:[0,0,1]
	v_pk_fma_f32 v[80:81], v[108:109], v[126:127], v[80:81] neg_lo:[0,0,1] neg_hi:[0,0,1]
	v_cvt_pk_bf16_f32 v71, v76, v77
	v_lshlrev_b64 v[76:77], 7, v[66:67]
	v_pk_fma_f32 v[78:79], v[94:95], v[112:113], v[78:79]
	v_pk_fma_f32 v[74:75], v[98:99], v[116:117], v[74:75]
	v_cvt_pk_bf16_f32 v70, v72, v73
	v_cvt_pk_bf16_f32 v72, v84, v85
	v_cvt_pk_bf16_f32 v73, v80, v81
	v_lshl_add_u64 v[76:77], v[138:139], 0, v[76:77]
	global_store_dwordx4 v[76:77], v[70:73], off
	s_nop 1
	v_cvt_pk_bf16_f32 v70, v82, v83
	v_cvt_pk_bf16_f32 v71, v78, v79
	v_cvt_pk_bf16_f32 v72, v86, v87
	v_cvt_pk_bf16_f32 v73, v74, v75
	global_store_dwordx4 v[76:77], v[70:73], off offset:64

.LBB0_1093:
	v_add_u32_e32 v50, 0x90, v150
	s_waitcnt lgkmcnt(0)
	v_ashrrev_i32_e32 v51, 31, v50
	s_and_b64 vcc, exec, s[10:11]
	v_fmamk_f32 v52, v238, 0x3a800000, v159
	v_rsq_f32_e32 v52, v52
	s_cbranch_vccnz .LBB0_1097
	s_and_b64 vcc, exec, s[8:9]
	s_cbranch_vccnz .LBB0_1096
	v_lshlrev_b32_e32 v53, 5, v50
	v_and_or_b32 v53, v53, s76, v154
	v_lshlrev_b32_e32 v53, 3, v53
	global_load_dwordx4 v[54:57], v53, s[26:27]
	global_load_dwordx4 v[58:61], v53, s[26:27] offset:16
	global_load_dwordx4 v[62:65], v53, s[26:27] offset:32
	global_load_dwordx4 v[66:69], v53, s[26:27] offset:48
	v_mov_b32_e32 v78, v48
	v_mov_b32_e32 v79, v41
	v_mov_b32_e32 v80, v40
	v_mov_b32_e32 v81, v49
	v_mov_b32_e32 v70, v46
	v_mov_b32_e32 v71, v39
	v_mov_b32_e32 v72, v38
	v_mov_b32_e32 v73, v47
	v_mov_b32_e32 v74, v42
	v_mov_b32_e32 v75, v35
	v_mov_b32_e32 v76, v34
	v_mov_b32_e32 v77, v43
	v_mov_b32_e32 v82, v44
	v_mov_b32_e32 v83, v37
	v_mov_b32_e32 v84, v36
	v_mov_b32_e32 v85, v45
	v_pk_mul_f32 v[78:79], v[78:79], v[52:53] op_sel_hi:[1,0]
	v_pk_mul_f32 v[80:81], v[80:81], v[52:53] op_sel_hi:[1,0]
	v_pk_mul_f32 v[70:71], v[70:71], v[52:53] op_sel_hi:[1,0]
	v_pk_mul_f32 v[72:73], v[72:73], v[52:53] op_sel_hi:[1,0]
	v_pk_mul_f32 v[74:75], v[74:75], v[52:53] op_sel_hi:[1,0]
	v_pk_mul_f32 v[76:77], v[76:77], v[52:53] op_sel_hi:[1,0]
	v_pk_mul_f32 v[82:83], v[82:83], v[52:53] op_sel_hi:[1,0]
	v_pk_mul_f32 v[84:85], v[84:85], v[52:53] op_sel_hi:[1,0]
	v_mov_b32_e32 v91, v81
	v_mov_b32_e32 v87, v73
	v_mov_b32_e32 v89, v77
	v_mov_b32_e32 v90, v78
	v_mov_b32_e32 v93, v85
	v_mov_b32_e32 v86, v70
	v_mov_b32_e32 v88, v74
	v_mov_b32_e32 v92, v82
	s_waitcnt vmcnt(3)
	v_mov_b32_e32 v102, v54
	v_mov_b32_e32 v104, v54
	s_waitcnt vmcnt(1)
	v_mov_b32_e32 v98, v63
	v_mov_b32_e32 v99, v64
	v_mov_b32_e32 v54, v62
	v_mov_b32_e32 v106, v62
	v_mov_b32_e32 v107, v64
	v_mov_b32_e32 v64, v63
	v_mov_b32_e32 v62, v58
	v_mov_b32_e32 v63, v61
	v_mov_b32_e32 v94, v55
	v_mov_b32_e32 v95, v56
	v_mov_b32_e32 v96, v59
	v_mov_b32_e32 v97, v60
	v_mov_b32_e32 v103, v57
	v_mov_b32_e32 v105, v56
	v_mov_b32_e32 v56, v55
	v_mov_b32_e32 v55, v65
	v_mov_b32_e32 v108, v58
	v_mov_b32_e32 v109, v60
	v_mov_b32_e32 v60, v59
	s_waitcnt vmcnt(0)
	v_mov_b32_e32 v58, v66
	v_mov_b32_e32 v59, v69
	v_pk_mul_f32 v[62:63], v[80:81], v[62:63]
	v_mov_b32_e32 v81, v79
	v_mov_b32_e32 v100, v67
	v_mov_b32_e32 v101, v68
	v_mov_b32_e32 v110, v66
	v_mov_b32_e32 v111, v68
	v_mov_b32_e32 v68, v67
	v_pk_mul_f32 v[66:67], v[72:73], v[102:103]
	v_mov_b32_e32 v73, v71
	v_pk_mul_f32 v[54:55], v[76:77], v[54:55]
	v_mov_b32_e32 v77, v75
	v_pk_mul_f32 v[58:59], v[84:85], v[58:59]
	v_mov_b32_e32 v85, v83
	v_pk_mul_f32 v[60:61], v[80:81], v[60:61]
	v_pk_fma_f32 v[66:67], v[70:71], v[94:95], v[66:67]
	v_pk_mul_f32 v[56:57], v[72:73], v[56:57]
	v_pk_fma_f32 v[70:71], v[74:75], v[98:99], v[54:55]
	v_pk_mul_f32 v[54:55], v[76:77], v[64:65]
	v_pk_mul_f32 v[64:65], v[84:85], v[68:69]
	v_pk_fma_f32 v[60:61], v[90:91], v[108:109], v[60:61] neg_lo:[0,0,1] neg_hi:[0,0,1]
	v_pk_fma_f32 v[56:57], v[86:87], v[104:105], v[56:57] neg_lo:[0,0,1] neg_hi:[0,0,1]
	v_pk_fma_f32 v[68:69], v[88:89], v[106:107], v[54:55] neg_lo:[0,0,1] neg_hi:[0,0,1]
	v_pk_fma_f32 v[64:65], v[92:93], v[110:111], v[64:65] neg_lo:[0,0,1] neg_hi:[0,0,1]
	v_cvt_pk_bf16_f32 v55, v60, v61
	v_lshlrev_b64 v[60:61], 7, v[50:51]
	v_pk_fma_f32 v[62:63], v[78:79], v[96:97], v[62:63]
	v_pk_fma_f32 v[58:59], v[82:83], v[100:101], v[58:59]
	v_cvt_pk_bf16_f32 v54, v56, v57
	v_cvt_pk_bf16_f32 v56, v68, v69
	v_cvt_pk_bf16_f32 v57, v64, v65
	v_lshl_add_u64 v[60:61], v[138:139], 0, v[60:61]
	global_store_dwordx4 v[60:61], v[54:57], off
	s_nop 1
	v_cvt_pk_bf16_f32 v54, v66, v67
	v_cvt_pk_bf16_f32 v55, v62, v63
	v_cvt_pk_bf16_f32 v56, v70, v71
	v_cvt_pk_bf16_f32 v57, v58, v59
	global_store_dwordx4 v[60:61], v[54:57], off offset:64

.LBB0_1101:
	v_add_u32_e32 v34, 0xa0, v150
	s_waitcnt lgkmcnt(0)
	v_ashrrev_i32_e32 v35, 31, v34
	s_and_b64 vcc, exec, s[10:11]
	v_fmamk_f32 v36, v239, 0x3a800000, v159
	v_rsq_f32_e32 v36, v36
	s_cbranch_vccnz .LBB0_1105
	s_and_b64 vcc, exec, s[8:9]
	s_cbranch_vccnz .LBB0_1104
	v_lshlrev_b32_e32 v37, 5, v34
	v_and_or_b32 v37, v37, s77, v154
	v_lshlrev_b32_e32 v37, 3, v37
	global_load_dwordx4 v[38:41], v37, s[26:27]
	global_load_dwordx4 v[42:45], v37, s[26:27] offset:16
	global_load_dwordx4 v[46:49], v37, s[26:27] offset:32
	global_load_dwordx4 v[50:53], v37, s[26:27] offset:48
	v_mov_b32_e32 v62, v32
	v_mov_b32_e32 v63, v25
	v_mov_b32_e32 v64, v24
	v_mov_b32_e32 v65, v33
	v_mov_b32_e32 v54, v30
	v_mov_b32_e32 v55, v23
	v_mov_b32_e32 v56, v22
	v_mov_b32_e32 v57, v31
	v_mov_b32_e32 v58, v26
	v_mov_b32_e32 v59, v19
	v_mov_b32_e32 v60, v18
	v_mov_b32_e32 v61, v27
	v_mov_b32_e32 v66, v28
	v_mov_b32_e32 v67, v21
	v_mov_b32_e32 v68, v20
	v_mov_b32_e32 v69, v29
	v_pk_mul_f32 v[62:63], v[62:63], v[36:37] op_sel_hi:[1,0]
	v_pk_mul_f32 v[64:65], v[64:65], v[36:37] op_sel_hi:[1,0]
	v_pk_mul_f32 v[54:55], v[54:55], v[36:37] op_sel_hi:[1,0]
	v_pk_mul_f32 v[56:57], v[56:57], v[36:37] op_sel_hi:[1,0]
	v_pk_mul_f32 v[58:59], v[58:59], v[36:37] op_sel_hi:[1,0]
	v_pk_mul_f32 v[60:61], v[60:61], v[36:37] op_sel_hi:[1,0]
	v_pk_mul_f32 v[66:67], v[66:67], v[36:37] op_sel_hi:[1,0]
	v_pk_mul_f32 v[68:69], v[68:69], v[36:37] op_sel_hi:[1,0]
	v_mov_b32_e32 v75, v65
	v_mov_b32_e32 v71, v57
	v_mov_b32_e32 v73, v61
	v_mov_b32_e32 v74, v62
	v_mov_b32_e32 v77, v69
	v_mov_b32_e32 v70, v54
	v_mov_b32_e32 v72, v58
	v_mov_b32_e32 v76, v66
	s_waitcnt vmcnt(3)
	v_mov_b32_e32 v86, v38
	v_mov_b32_e32 v88, v38
	s_waitcnt vmcnt(1)
	v_mov_b32_e32 v82, v47
	v_mov_b32_e32 v83, v48
	v_mov_b32_e32 v38, v46
	v_mov_b32_e32 v90, v46
	v_mov_b32_e32 v91, v48
	v_mov_b32_e32 v48, v47
	v_mov_b32_e32 v46, v42
	v_mov_b32_e32 v47, v45
	v_mov_b32_e32 v78, v39
	v_mov_b32_e32 v79, v40
	v_mov_b32_e32 v80, v43
	v_mov_b32_e32 v81, v44
	v_mov_b32_e32 v87, v41
	v_mov_b32_e32 v89, v40
	v_mov_b32_e32 v40, v39
	v_mov_b32_e32 v39, v49
	v_mov_b32_e32 v92, v42
	v_mov_b32_e32 v93, v44
	v_mov_b32_e32 v44, v43
	s_waitcnt vmcnt(0)
	v_mov_b32_e32 v42, v50
	v_mov_b32_e32 v43, v53
	v_pk_mul_f32 v[46:47], v[64:65], v[46:47]
	v_mov_b32_e32 v65, v63
	v_mov_b32_e32 v84, v51
	v_mov_b32_e32 v85, v52
	v_mov_b32_e32 v94, v50
	v_mov_b32_e32 v95, v52
	v_mov_b32_e32 v52, v51
	v_pk_mul_f32 v[50:51], v[56:57], v[86:87]
	v_mov_b32_e32 v57, v55
	v_pk_mul_f32 v[38:39], v[60:61], v[38:39]
	v_mov_b32_e32 v61, v59
	v_pk_mul_f32 v[42:43], v[68:69], v[42:43]
	v_mov_b32_e32 v69, v67
	v_pk_mul_f32 v[44:45], v[64:65], v[44:45]
	v_pk_fma_f32 v[50:51], v[54:55], v[78:79], v[50:51]
	v_pk_mul_f32 v[40:41], v[56:57], v[40:41]
	v_pk_fma_f32 v[54:55], v[58:59], v[82:83], v[38:39]
	v_pk_mul_f32 v[38:39], v[60:61], v[48:49]
	v_pk_mul_f32 v[48:49], v[68:69], v[52:53]
	v_pk_fma_f32 v[44:45], v[74:75], v[92:93], v[44:45] neg_lo:[0,0,1] neg_hi:[0,0,1]
	v_pk_fma_f32 v[40:41], v[70:71], v[88:89], v[40:41] neg_lo:[0,0,1] neg_hi:[0,0,1]
	v_pk_fma_f32 v[52:53], v[72:73], v[90:91], v[38:39] neg_lo:[0,0,1] neg_hi:[0,0,1]
	v_pk_fma_f32 v[48:49], v[76:77], v[94:95], v[48:49] neg_lo:[0,0,1] neg_hi:[0,0,1]
	v_cvt_pk_bf16_f32 v39, v44, v45
	v_lshlrev_b64 v[44:45], 7, v[34:35]
	v_pk_fma_f32 v[46:47], v[62:63], v[80:81], v[46:47]
	v_pk_fma_f32 v[42:43], v[66:67], v[84:85], v[42:43]
	v_cvt_pk_bf16_f32 v38, v40, v41
	v_cvt_pk_bf16_f32 v40, v52, v53
	v_cvt_pk_bf16_f32 v41, v48, v49
	v_lshl_add_u64 v[44:45], v[138:139], 0, v[44:45]
	global_store_dwordx4 v[44:45], v[38:41], off
	s_nop 1
	v_cvt_pk_bf16_f32 v38, v50, v51
	v_cvt_pk_bf16_f32 v39, v46, v47
	v_cvt_pk_bf16_f32 v40, v54, v55
	v_cvt_pk_bf16_f32 v41, v42, v43
	global_store_dwordx4 v[44:45], v[38:41], off offset:64

.LBB0_1109:
	v_add_u32_e32 v18, 0xb0, v150
	s_waitcnt lgkmcnt(0)
	v_ashrrev_i32_e32 v19, 31, v18
	s_and_b64 vcc, exec, s[10:11]
	v_fmamk_f32 v20, v240, 0x3a800000, v159
	v_rsq_f32_e32 v20, v20
	s_cbranch_vccnz .LBB0_1114
	s_and_b64 vcc, exec, s[8:9]
	s_cbranch_vccnz .LBB0_1112
	v_lshlrev_b32_e32 v21, 5, v18
	v_and_or_b32 v21, v21, s78, v154
	v_lshlrev_b32_e32 v21, 3, v21
	global_load_dwordx4 v[22:25], v21, s[26:27]
	global_load_dwordx4 v[26:29], v21, s[26:27] offset:16
	global_load_dwordx4 v[30:33], v21, s[26:27] offset:32
	global_load_dwordx4 v[34:37], v21, s[26:27] offset:48
	v_mov_b32_e32 v46, v16
	v_mov_b32_e32 v47, v9
	v_mov_b32_e32 v48, v8
	v_mov_b32_e32 v49, v17
	v_mov_b32_e32 v38, v14
	v_mov_b32_e32 v39, v7
	v_mov_b32_e32 v40, v6
	v_mov_b32_e32 v41, v15
	v_mov_b32_e32 v42, v10
	v_mov_b32_e32 v43, v3
	v_mov_b32_e32 v44, v2
	v_mov_b32_e32 v45, v11
	v_mov_b32_e32 v50, v12
	v_mov_b32_e32 v51, v5
	v_mov_b32_e32 v52, v4
	v_mov_b32_e32 v53, v13
	v_pk_mul_f32 v[46:47], v[46:47], v[20:21] op_sel_hi:[1,0]
	v_pk_mul_f32 v[48:49], v[48:49], v[20:21] op_sel_hi:[1,0]
	v_pk_mul_f32 v[38:39], v[38:39], v[20:21] op_sel_hi:[1,0]
	v_pk_mul_f32 v[40:41], v[40:41], v[20:21] op_sel_hi:[1,0]
	v_pk_mul_f32 v[42:43], v[42:43], v[20:21] op_sel_hi:[1,0]
	v_pk_mul_f32 v[44:45], v[44:45], v[20:21] op_sel_hi:[1,0]
	v_pk_mul_f32 v[50:51], v[50:51], v[20:21] op_sel_hi:[1,0]
	v_pk_mul_f32 v[52:53], v[52:53], v[20:21] op_sel_hi:[1,0]
	v_mov_b32_e32 v59, v49
	v_mov_b32_e32 v55, v41
	v_mov_b32_e32 v57, v45
	v_mov_b32_e32 v58, v46
	v_mov_b32_e32 v61, v53
	v_mov_b32_e32 v54, v38
	v_mov_b32_e32 v56, v42
	v_mov_b32_e32 v60, v50
	s_waitcnt vmcnt(3)
	v_mov_b32_e32 v70, v22
	v_mov_b32_e32 v72, v22
	s_waitcnt vmcnt(1)
	v_mov_b32_e32 v66, v31
	v_mov_b32_e32 v67, v32
	v_mov_b32_e32 v22, v30
	v_mov_b32_e32 v74, v30
	v_mov_b32_e32 v75, v32
	v_mov_b32_e32 v32, v31
	v_mov_b32_e32 v30, v26
	v_mov_b32_e32 v31, v29
	v_mov_b32_e32 v62, v23
	v_mov_b32_e32 v63, v24
	v_mov_b32_e32 v64, v27
	v_mov_b32_e32 v65, v28
	v_mov_b32_e32 v71, v25
	v_mov_b32_e32 v73, v24
	v_mov_b32_e32 v24, v23
	v_mov_b32_e32 v23, v33
	v_mov_b32_e32 v76, v26
	v_mov_b32_e32 v77, v28
	v_mov_b32_e32 v28, v27
	s_waitcnt vmcnt(0)
	v_mov_b32_e32 v26, v34
	v_mov_b32_e32 v27, v37
	v_pk_mul_f32 v[30:31], v[48:49], v[30:31]
	v_mov_b32_e32 v49, v47
	v_mov_b32_e32 v68, v35
	v_mov_b32_e32 v69, v36
	v_mov_b32_e32 v78, v34
	v_mov_b32_e32 v79, v36
	v_mov_b32_e32 v36, v35
	v_pk_mul_f32 v[34:35], v[40:41], v[70:71]
	v_mov_b32_e32 v41, v39
	v_pk_mul_f32 v[22:23], v[44:45], v[22:23]
	v_mov_b32_e32 v45, v43
	v_pk_mul_f32 v[26:27], v[52:53], v[26:27]
	v_mov_b32_e32 v53, v51
	v_pk_mul_f32 v[28:29], v[48:49], v[28:29]
	v_pk_fma_f32 v[34:35], v[38:39], v[62:63], v[34:35]
	v_pk_mul_f32 v[24:25], v[40:41], v[24:25]
	v_pk_fma_f32 v[38:39], v[42:43], v[66:67], v[22:23]
	v_pk_mul_f32 v[22:23], v[44:45], v[32:33]
	v_pk_mul_f32 v[32:33], v[52:53], v[36:37]
	v_pk_fma_f32 v[28:29], v[58:59], v[76:77], v[28:29] neg_lo:[0,0,1] neg_hi:[0,0,1]
	v_pk_fma_f32 v[24:25], v[54:55], v[72:73], v[24:25] neg_lo:[0,0,1] neg_hi:[0,0,1]
	v_pk_fma_f32 v[36:37], v[56:57], v[74:75], v[22:23] neg_lo:[0,0,1] neg_hi:[0,0,1]
	v_pk_fma_f32 v[32:33], v[60:61], v[78:79], v[32:33] neg_lo:[0,0,1] neg_hi:[0,0,1]
	v_cvt_pk_bf16_f32 v23, v28, v29
	v_lshlrev_b64 v[28:29], 7, v[18:19]
	v_pk_fma_f32 v[30:31], v[46:47], v[64:65], v[30:31]
	v_pk_fma_f32 v[26:27], v[50:51], v[68:69], v[26:27]
	v_cvt_pk_bf16_f32 v22, v24, v25
	v_cvt_pk_bf16_f32 v24, v36, v37
	v_cvt_pk_bf16_f32 v25, v32, v33
	v_lshl_add_u64 v[28:29], v[138:139], 0, v[28:29]
	global_store_dwordx4 v[28:29], v[22:25], off
	s_nop 1
	v_cvt_pk_bf16_f32 v22, v34, v35
	v_cvt_pk_bf16_f32 v23, v30, v31
	v_cvt_pk_bf16_f32 v24, v38, v39
	v_cvt_pk_bf16_f32 v25, v26, v27
	global_store_dwordx4 v[28:29], v[22:25], off offset:64

.LBB0_1999:
.LBB0_2000:
	s_cmp_lt_i32 s20, 17
	s_cselect_b64 s[4:5], -1, 0
	s_and_b64 s[2:3], s[4:5], s[2:3]
	s_andn2_b64 vcc, exec, s[2:3]
	s_cbranch_vccnz .LBB0_2004
	s_mov_b64 s[2:3], s[0:1]
	s_mov_b64 s[4:5], s[0:1]
	s_cmpk_gt_i32 s28, 0x7fff
	s_cbranch_scc1 .LBB0_2004
	s_load_dwordx2 s[6:7], s[0:1], 0x98
	s_load_dwordx2 s[8:9], s[2:3], 0xa0
	s_load_dwordx2 s[10:11], s[4:5], 0xa8
	s_ashr_i32 s29, s28, 31
	s_lshl_b64 s[0:1], s[28:29], 2
	v_lshlrev_b32_e32 v0, 4, v242
	v_mov_b32_e32 v1, 0
	s_waitcnt lgkmcnt(0)
	s_add_u32 s0, s10, s0
	s_addc_u32 s1, s11, s1
	s_add_u32 s0, s0, 0x100000
	s_addc_u32 s1, s1, 0
	s_ashr_i32 s31, s30, 31
	s_lshl_b64 s[2:3], s[30:31], 2
	s_lshl_b64 s[4:5], s[28:29], 12
	s_add_u32 s4, s8, s4
	s_addc_u32 s5, s9, s5
	v_lshl_add_u64 v[4:5], s[4:5], 0, v[0:1]
	s_mov_b64 s[4:5], 0x800
	v_lshl_add_u64 v[2:3], s[6:7], 0, v[0:1]
	v_lshl_add_u64 v[4:5], v[4:5], 0, s[4:5]
	s_lshl_b64 s[4:5], s[30:31], 12
	v_mov_b32_e32 v0, 0x358637bd
	global_load_dwordx4 v[20:23], v[2:3], off
	global_load_dwordx4 v[24:27], v[2:3], off offset:1024
	global_load_dwordx4 v[28:31], v[2:3], off offset:2048
	global_load_dwordx4 v[32:35], v[2:3], off offset:3072
	global_load_dword v18, v1, s[0:1]
	global_load_dwordx4 v[36:39], v[4:5], off offset:-2048
	global_load_dwordx4 v[40:43], v[4:5], off offset:-1024
	global_load_dwordx4 v[44:47], v[4:5], off
	global_load_dwordx4 v[48:51], v[4:5], off offset:1024
.Lfin_A:
	v_lshl_add_u64 v[6:7], v[4:5], 0, s[4:5]
	s_add_i32 s28, s28, s30
	s_add_u32 s0, s0, s2
	s_addc_u32 s1, s1, s3
	s_cmp_lt_i32 s28, 0x8000
	s_cbranch_scc0 .Lfin_A_last
	global_load_dword v68, v1, s[0:1]
	global_load_dwordx4 v[52:55], v[6:7], off offset:-2048
	global_load_dwordx4 v[56:59], v[6:7], off offset:-1024
	global_load_dwordx4 v[60:63], v[6:7], off
	global_load_dwordx4 v[64:67], v[6:7], off offset:1024
	s_waitcnt vmcnt(5)
	v_fmamk_f32 v18, v18, 0x3a800000, v0
	v_rsq_f32_e32 v18, v18
	s_nop 0
	v_pk_mul_f32 v[38:39], v[18:19], v[38:39] op_sel_hi:[0,1]
	v_pk_mul_f32 v[36:37], v[18:19], v[36:37] op_sel_hi:[0,1]
	v_pk_mul_f32 v[38:39], v[38:39], v[22:23]
	v_pk_mul_f32 v[36:37], v[36:37], v[20:21]
	global_store_dwordx4 v[4:5], v[36:39], off offset:-2048 nt
	v_pk_mul_f32 v[42:43], v[18:19], v[42:43] op_sel_hi:[0,1]
	v_pk_mul_f32 v[40:41], v[18:19], v[40:41] op_sel_hi:[0,1]
	v_pk_mul_f32 v[42:43], v[42:43], v[26:27]
	v_pk_mul_f32 v[40:41], v[40:41], v[24:25]
	global_store_dwordx4 v[4:5], v[40:43], off offset:-1024 nt
	v_pk_mul_f32 v[46:47], v[18:19], v[46:47] op_sel_hi:[0,1]
	v_pk_mul_f32 v[44:45], v[18:19], v[44:45] op_sel_hi:[0,1]
	v_pk_mul_f32 v[46:47], v[46:47], v[30:31]
	v_pk_mul_f32 v[44:45], v[44:45], v[28:29]
	global_store_dwordx4 v[4:5], v[44:47], off nt
	v_pk_mul_f32 v[50:51], v[18:19], v[50:51] op_sel_hi:[0,1]
	v_pk_mul_f32 v[48:49], v[18:19], v[48:49] op_sel_hi:[0,1]
	v_pk_mul_f32 v[50:51], v[50:51], v[34:35]
	v_pk_mul_f32 v[48:49], v[48:49], v[32:33]
	global_store_dwordx4 v[4:5], v[48:51], off offset:1024 nt
	v_lshl_add_u64 v[4:5], v[6:7], 0, s[4:5]
	s_add_i32 s28, s28, s30
	s_add_u32 s0, s0, s2
	s_addc_u32 s1, s1, s3
	s_cmp_lt_i32 s28, 0x8000
	s_cbranch_scc0 .Lfin_B_last
	global_load_dword v18, v1, s[0:1]
	global_load_dwordx4 v[36:39], v[4:5], off offset:-2048
	global_load_dwordx4 v[40:43], v[4:5], off offset:-1024
	global_load_dwordx4 v[44:47], v[4:5], off
	global_load_dwordx4 v[48:51], v[4:5], off offset:1024
	s_waitcnt vmcnt(5)
	v_fmamk_f32 v68, v68, 0x3a800000, v0
	v_rsq_f32_e32 v68, v68
	s_nop 0
	v_pk_mul_f32 v[54:55], v[68:69], v[54:55] op_sel_hi:[0,1]
	v_pk_mul_f32 v[52:53], v[68:69], v[52:53] op_sel_hi:[0,1]
	v_pk_mul_f32 v[54:55], v[54:55], v[22:23]
	v_pk_mul_f32 v[52:53], v[52:53], v[20:21]
	global_store_dwordx4 v[6:7], v[52:55], off offset:-2048 nt
	v_pk_mul_f32 v[58:59], v[68:69], v[58:59] op_sel_hi:[0,1]
	v_pk_mul_f32 v[56:57], v[68:69], v[56:57] op_sel_hi:[0,1]
	v_pk_mul_f32 v[58:59], v[58:59], v[26:27]
	v_pk_mul_f32 v[56:57], v[56:57], v[24:25]
	global_store_dwordx4 v[6:7], v[56:59], off offset:-1024 nt
	v_pk_mul_f32 v[62:63], v[68:69], v[62:63] op_sel_hi:[0,1]
	v_pk_mul_f32 v[60:61], v[68:69], v[60:61] op_sel_hi:[0,1]
	v_pk_mul_f32 v[62:63], v[62:63], v[30:31]
	v_pk_mul_f32 v[60:61], v[60:61], v[28:29]
	global_store_dwordx4 v[6:7], v[60:63], off nt
	v_pk_mul_f32 v[66:67], v[68:69], v[66:67] op_sel_hi:[0,1]
	v_pk_mul_f32 v[64:65], v[68:69], v[64:65] op_sel_hi:[0,1]
	v_pk_mul_f32 v[66:67], v[66:67], v[34:35]
	v_pk_mul_f32 v[64:65], v[64:65], v[32:33]
	global_store_dwordx4 v[6:7], v[64:67], off offset:1024 nt
	s_branch .Lfin_A
.Lfin_A_last:
	s_waitcnt vmcnt(0)
	v_fmamk_f32 v18, v18, 0x3a800000, v0
	v_rsq_f32_e32 v18, v18
	s_nop 0
	v_pk_mul_f32 v[38:39], v[18:19], v[38:39] op_sel_hi:[0,1]
	v_pk_mul_f32 v[36:37], v[18:19], v[36:37] op_sel_hi:[0,1]
	v_pk_mul_f32 v[38:39], v[38:39], v[22:23]
	v_pk_mul_f32 v[36:37], v[36:37], v[20:21]
	global_store_dwordx4 v[4:5], v[36:39], off offset:-2048 nt
	v_pk_mul_f32 v[42:43], v[18:19], v[42:43] op_sel_hi:[0,1]
	v_pk_mul_f32 v[40:41], v[18:19], v[40:41] op_sel_hi:[0,1]
	v_pk_mul_f32 v[42:43], v[42:43], v[26:27]
	v_pk_mul_f32 v[40:41], v[40:41], v[24:25]
	global_store_dwordx4 v[4:5], v[40:43], off offset:-1024 nt
	v_pk_mul_f32 v[46:47], v[18:19], v[46:47] op_sel_hi:[0,1]
	v_pk_mul_f32 v[44:45], v[18:19], v[44:45] op_sel_hi:[0,1]
	v_pk_mul_f32 v[46:47], v[46:47], v[30:31]
	v_pk_mul_f32 v[44:45], v[44:45], v[28:29]
	global_store_dwordx4 v[4:5], v[44:47], off nt
	v_pk_mul_f32 v[50:51], v[18:19], v[50:51] op_sel_hi:[0,1]
	v_pk_mul_f32 v[48:49], v[18:19], v[48:49] op_sel_hi:[0,1]
	v_pk_mul_f32 v[50:51], v[50:51], v[34:35]
	v_pk_mul_f32 v[48:49], v[48:49], v[32:33]
	global_store_dwordx4 v[4:5], v[48:51], off offset:1024 nt
	s_branch .LBB0_2004
.Lfin_B_last:
	s_waitcnt vmcnt(0)
	v_fmamk_f32 v68, v68, 0x3a800000, v0
	v_rsq_f32_e32 v68, v68
	s_nop 0
	v_pk_mul_f32 v[54:55], v[68:69], v[54:55] op_sel_hi:[0,1]
	v_pk_mul_f32 v[52:53], v[68:69], v[52:53] op_sel_hi:[0,1]
	v_pk_mul_f32 v[54:55], v[54:55], v[22:23]
	v_pk_mul_f32 v[52:53], v[52:53], v[20:21]
	global_store_dwordx4 v[6:7], v[52:55], off offset:-2048 nt
	v_pk_mul_f32 v[58:59], v[68:69], v[58:59] op_sel_hi:[0,1]
	v_pk_mul_f32 v[56:57], v[68:69], v[56:57] op_sel_hi:[0,1]
	v_pk_mul_f32 v[58:59], v[58:59], v[26:27]
	v_pk_mul_f32 v[56:57], v[56:57], v[24:25]
	global_store_dwordx4 v[6:7], v[56:59], off offset:-1024 nt
	v_pk_mul_f32 v[62:63], v[68:69], v[62:63] op_sel_hi:[0,1]
	v_pk_mul_f32 v[60:61], v[68:69], v[60:61] op_sel_hi:[0,1]
	v_pk_mul_f32 v[62:63], v[62:63], v[30:31]
	v_pk_mul_f32 v[60:61], v[60:61], v[28:29]
	global_store_dwordx4 v[6:7], v[60:63], off nt
	v_pk_mul_f32 v[66:67], v[68:69], v[66:67] op_sel_hi:[0,1]
	v_pk_mul_f32 v[64:65], v[68:69], v[64:65] op_sel_hi:[0,1]
	v_pk_mul_f32 v[66:67], v[66:67], v[34:35]
	v_pk_mul_f32 v[64:65], v[64:65], v[32:33]
	global_store_dwordx4 v[6:7], v[64:67], off offset:1024 nt
